# merge GEMM: XCDs 4-7 start the phase ~10us later (s_sleep) so the two halves' gate-load/epilogue bursts do not coincide
# speedup vs baseline: 1.0032x; 1.0032x over previous
.LBB0_567:
	s_cmp_lt_i32 s76, 8
	s_cselect_b64 s[12:13], -1, 0
	s_cmp_gt_i32 s77, 7
	s_cselect_b64 s[4:5], -1, 0
	s_and_b64 s[4:5], s[12:13], s[4:5]
	s_andn2_b64 vcc, exec, s[4:5]
	v_bfe_u32 v223, v196, 2, 2
	s_cbranch_vccnz .LBB0_692
	s_cmpk_lt_i32 s2, 0x400
	s_cselect_b64 s[8:9], -1, 0
	s_cmpk_gt_i32 s2, 0x3ff
	s_mov_b64 s[6:7], s[0:1]
	v_readfirstlane_b32 s20, v196
	s_waitcnt vmcnt(0) lgkmcnt(0)
	s_barrier
	s_cbranch_scc1 .LBB0_570
	s_bfe_u32 s99, s2, 0x10002
	s_cmp_eq_u32 s99, 0
	s_cbranch_scc1 .Lstg7_done
.Lstg7_loop:
	s_sleep 127
	s_sleep 127
	s_sleep 127
	s_sub_u32 s99, s99, 1
	s_cmp_lg_u32 s99, 0
	s_cbranch_scc1 .Lstg7_loop
